# postscan output-gate tile: g_up fragments double-buffered across column blocks
# baseline (speedup 1.0000x reference)
.LBB0_133:
	s_or_b64 exec, exec, s[8:9]
	v_ashrrev_i32_e32 v185, 31, v184
	v_lshlrev_b64 v[28:29], 11, v[184:185]
	v_lshl_add_u64 v[188:189], s[4:5], 0, v[28:29]
	v_mov_b64_e32 v[28:29], s[4:5]
	s_movk_i32 s3, 0x1c00
	v_mad_i64_i32 v[190:191], s[6:7], v184, s3, v[28:29]
	s_waitcnt vmcnt(0)
	v_cvt_f32_f16_e32 v28, v16
	v_cvt_f32_f16_sdwa v29, v24 dst_sel:DWORD dst_unused:UNUSED_PAD src0_sel:WORD_1
	v_mov_b32_e32 v211, v184
	v_mul_f32_e32 v28, v4, v28
	v_fma_mix_f32 v28, v1, v20, v28 op_sel_hi:[0,1,0]
	v_fma_mix_f32 v28, v3, v24, v28 op_sel_hi:[0,1,0]
	v_mul_f32_e32 v28, 0xbfb8aa3b, v28
	v_exp_f32_e32 v28, v28
	v_cvt_f32_f16_sdwa v24, v21 dst_sel:DWORD dst_unused:UNUSED_PAD src0_sel:WORD_1
	v_add_f32_e32 v28, 1.0, v28
	v_rcp_f32_e32 v30, v28
	v_cvt_f32_f16_sdwa v28, v20 dst_sel:DWORD dst_unused:UNUSED_PAD src0_sel:WORD_1
	v_pk_mul_f32 v[28:29], v[12:13], v[28:29]
	s_nop 0
	v_fma_mix_f32 v16, v5, v16, v28 op_sel:[0,1,0] op_sel_hi:[0,1,0]
	v_add_f32_e32 v16, v16, v29
	v_mul_f32_e32 v16, 0xbfb8aa3b, v16
	v_exp_f32_e32 v16, v16
	v_cvt_f32_f16_e32 v29, v25
	v_cvt_f32_f16_e32 v28, v21
	v_cvt_f32_f16_sdwa v25, v25 dst_sel:DWORD dst_unused:UNUSED_PAD src0_sel:WORD_1
	v_add_f32_e32 v16, 1.0, v16
	v_rcp_f32_e32 v31, v16
	v_pk_mul_f32 v[28:29], v[180:181], v[28:29]
	v_pk_mul_f32 v[20:21], v[14:15], v[24:25]
	v_fma_mix_f32 v16, v6, v17, v28 op_sel_hi:[0,1,0]
	v_add_f32_e32 v16, v16, v29
	v_mul_f32_e32 v16, 0xbfb8aa3b, v16
	v_exp_f32_e32 v16, v16
	s_nop 0
	v_add_f32_e32 v16, 1.0, v16
	v_rcp_f32_e32 v28, v16
	v_fma_mix_f32 v16, v7, v17, v20 op_sel:[0,1,0] op_sel_hi:[0,1,0]
	v_add_f32_e32 v16, v16, v21
	v_mul_f32_e32 v16, 0xbfb8aa3b, v16
	v_exp_f32_e32 v16, v16
	v_cvt_f32_f16_e32 v17, v26
	v_add_f32_e32 v16, 1.0, v16
	v_rcp_f32_e32 v20, v16
	v_cvt_f32_f16_e32 v16, v22
	v_pk_mul_f32 v[16:17], v[178:179], v[16:17]
	s_nop 0
	v_fma_mix_f32 v16, v8, v18, v16 op_sel_hi:[0,1,0]
	v_add_f32_e32 v16, v16, v17
	v_mul_f32_e32 v16, 0xbfb8aa3b, v16
	v_exp_f32_e32 v16, v16
	v_cvt_f32_f16_sdwa v17, v26 dst_sel:DWORD dst_unused:UNUSED_PAD src0_sel:WORD_1
	v_add_f32_e32 v16, 1.0, v16
	v_rcp_f32_e32 v21, v16
	v_cvt_f32_f16_sdwa v16, v22 dst_sel:DWORD dst_unused:UNUSED_PAD src0_sel:WORD_1
	v_pk_mul_f32 v[16:17], v[156:157], v[16:17]
	s_nop 0
	v_fma_mix_f32 v16, v9, v18, v16 op_sel:[0,1,0] op_sel_hi:[0,1,0]
	v_add_f32_e32 v16, v16, v17
	v_mul_f32_e32 v16, 0xbfb8aa3b, v16
	v_exp_f32_e32 v16, v16
	v_cvt_f32_f16_e32 v17, v27
	v_add_f32_e32 v16, 1.0, v16
	v_rcp_f32_e32 v18, v16
	v_cvt_f32_f16_e32 v16, v23
	v_cvt_pk_f16_f32 v18, v21, v18
	v_pk_mul_f32 v[16:17], v[176:177], v[16:17]
	s_nop 0
	v_fma_mix_f32 v16, v10, v19, v16 op_sel_hi:[0,1,0]
	v_add_f32_e32 v16, v16, v17
	v_mul_f32_e32 v16, 0xbfb8aa3b, v16
	v_exp_f32_e32 v16, v16
	v_cvt_f32_f16_sdwa v17, v27 dst_sel:DWORD dst_unused:UNUSED_PAD src0_sel:WORD_1
	v_add_f32_e32 v16, 1.0, v16
	v_rcp_f32_e32 v22, v16
	v_cvt_f32_f16_sdwa v16, v23 dst_sel:DWORD dst_unused:UNUSED_PAD src0_sel:WORD_1
	v_pk_mul_f32 v[16:17], v[158:159], v[16:17]
	s_nop 0
	v_fma_mix_f32 v16, v11, v19, v16 op_sel:[0,1,0] op_sel_hi:[0,1,0]
	v_add_f32_e32 v16, v16, v17
	v_mul_f32_e32 v16, 0xbfb8aa3b, v16
	v_exp_f32_e32 v16, v16
	v_cvt_pk_f16_f32 v17, v28, v20
	v_add_f32_e32 v16, 1.0, v16
	v_rcp_f32_e32 v16, v16
	s_nop 0
	v_cvt_pk_f16_f32 v19, v22, v16
	v_cvt_pk_f16_f32 v16, v30, v31
	ds_write_b128 v207, v[16:19] offset:49152
	s_waitcnt lgkmcnt(0)
	s_barrier
	ds_read_b128 v[40:43], v208 offset:49152
	ds_read_b128 v[32:35], v208 offset:49216
	ds_read_b128 v[24:27], v208 offset:49280
	ds_read_b128 v[20:23], v208 offset:49344
	ds_read_b128 v[44:47], v208 offset:53504
	ds_read_b128 v[36:39], v208 offset:53568
	ds_read_b128 v[28:31], v208 offset:53632
	ds_read_b128 v[16:19], v208 offset:53696
	global_load_dwordx4 v[60:63], v[160:161], off
	global_load_dwordx4 v[64:67], v[160:161], off offset:64
	global_load_dwordx4 v[68:71], v[160:161], off offset:128
	global_load_dwordx4 v[72:75], v[160:161], off offset:192
	global_load_dwordx4 v[76:79], v[162:163], off
	global_load_dwordx4 v[80:83], v[162:163], off offset:64
	global_load_dwordx4 v[84:87], v[162:163], off offset:128
	global_load_dwordx4 v[88:91], v[162:163], off offset:192
	s_waitcnt vmcnt(4) lgkmcnt(0)
	v_mfma_f32_16x16x32_f16 v[52:55], v[40:43], v[60:63], 0
	v_mfma_f32_16x16x32_f16 v[48:51], v[44:47], v[60:63], 0
	v_mfma_f32_16x16x32_f16 v[52:55], v[32:35], v[64:67], v[52:55]
	v_mfma_f32_16x16x32_f16 v[48:51], v[36:39], v[64:67], v[48:51]
	v_mfma_f32_16x16x32_f16 v[52:55], v[24:27], v[68:71], v[52:55]
	v_mfma_f32_16x16x32_f16 v[48:51], v[28:31], v[68:71], v[48:51]
	v_mfma_f32_16x16x32_f16 v[52:55], v[20:23], v[72:75], v[52:55]
	v_mfma_f32_16x16x32_f16 v[48:51], v[16:19], v[72:75], v[48:51]
	global_load_dwordx4 v[60:63], v[164:165], off
	global_load_dwordx4 v[64:67], v[164:165], off offset:64
	global_load_dwordx4 v[68:71], v[164:165], off offset:128
	global_load_dwordx4 v[72:75], v[164:165], off offset:192
	s_nop 7
	s_nop 1
	v_cvt_f16_f32_e32 v92, v52
	v_cvt_f16_f32_e32 v96, v48
	v_cvt_f16_f32_e32 v93, v53
	v_cvt_f16_f32_e32 v97, v49
	v_cvt_f16_f32_e32 v94, v54
	v_cvt_f16_f32_e32 v98, v50
	v_cvt_f16_f32_e32 v95, v55
	v_cvt_f16_f32_e32 v99, v51
	ds_write_b16 v200, v92 offset:57856
	ds_write_b16 v201, v96 offset:32768
	ds_write_b16 v200, v93 offset:59904
	ds_write_b16 v202, v97 offset:32768
	ds_write_b16 v200, v94 offset:61952
	ds_write_b16 v203, v98 offset:32768
	ds_write_b16 v200, v95 offset:64000
	ds_write_b16 v204, v99 offset:32768
	s_waitcnt vmcnt(4)
	v_mfma_f32_16x16x32_f16 v[52:55], v[40:43], v[76:79], 0
	v_mfma_f32_16x16x32_f16 v[48:51], v[44:47], v[76:79], 0
	v_mfma_f32_16x16x32_f16 v[52:55], v[32:35], v[80:83], v[52:55]
	v_mfma_f32_16x16x32_f16 v[48:51], v[36:39], v[80:83], v[48:51]
	v_mfma_f32_16x16x32_f16 v[52:55], v[24:27], v[84:87], v[52:55]
	v_mfma_f32_16x16x32_f16 v[48:51], v[28:31], v[84:87], v[48:51]
	v_mfma_f32_16x16x32_f16 v[52:55], v[20:23], v[88:91], v[52:55]
	v_mfma_f32_16x16x32_f16 v[48:51], v[16:19], v[88:91], v[48:51]
	global_load_dwordx4 v[76:79], v[166:167], off
	global_load_dwordx4 v[80:83], v[166:167], off offset:64
	global_load_dwordx4 v[84:87], v[166:167], off offset:128
	global_load_dwordx4 v[88:91], v[166:167], off offset:192
	s_nop 7
	s_nop 1
	v_cvt_f16_f32_e32 v92, v52
	v_cvt_f16_f32_e32 v96, v48
	v_cvt_f16_f32_e32 v93, v53
	v_cvt_f16_f32_e32 v97, v49
	v_cvt_f16_f32_e32 v94, v54
	v_cvt_f16_f32_e32 v98, v50
	v_cvt_f16_f32_e32 v95, v55
	v_cvt_f16_f32_e32 v99, v51
	ds_write_b16 v200, v92 offset:57888
	ds_write_b16 v201, v96 offset:32800
	ds_write_b16 v200, v93 offset:59936
	ds_write_b16 v202, v97 offset:32800
	ds_write_b16 v200, v94 offset:61984
	ds_write_b16 v203, v98 offset:32800
	ds_write_b16 v200, v95 offset:64032
	ds_write_b16 v204, v99 offset:32800
	s_waitcnt vmcnt(4)
	v_mfma_f32_16x16x32_f16 v[52:55], v[40:43], v[60:63], 0
	v_mfma_f32_16x16x32_f16 v[48:51], v[44:47], v[60:63], 0
	v_mfma_f32_16x16x32_f16 v[52:55], v[32:35], v[64:67], v[52:55]
	v_mfma_f32_16x16x32_f16 v[48:51], v[36:39], v[64:67], v[48:51]
	v_mfma_f32_16x16x32_f16 v[52:55], v[24:27], v[68:71], v[52:55]
	v_mfma_f32_16x16x32_f16 v[48:51], v[28:31], v[68:71], v[48:51]
	v_mfma_f32_16x16x32_f16 v[52:55], v[20:23], v[72:75], v[52:55]
	v_mfma_f32_16x16x32_f16 v[48:51], v[16:19], v[72:75], v[48:51]
	global_load_dwordx4 v[60:63], v[168:169], off
	global_load_dwordx4 v[64:67], v[168:169], off offset:64
	global_load_dwordx4 v[68:71], v[168:169], off offset:128
	global_load_dwordx4 v[72:75], v[168:169], off offset:192
	s_nop 7
	s_nop 1
	v_cvt_f16_f32_e32 v92, v52
	v_cvt_f16_f32_e32 v96, v48
	v_cvt_f16_f32_e32 v93, v53
	v_cvt_f16_f32_e32 v97, v49
	v_cvt_f16_f32_e32 v94, v54
	v_cvt_f16_f32_e32 v98, v50
	v_cvt_f16_f32_e32 v95, v55
	v_cvt_f16_f32_e32 v99, v51
	ds_write_b16 v200, v92 offset:57920
	ds_write_b16 v201, v96 offset:32832
	ds_write_b16 v200, v93 offset:59968
	ds_write_b16 v202, v97 offset:32832
	ds_write_b16 v200, v94 offset:62016
	ds_write_b16 v203, v98 offset:32832
	ds_write_b16 v200, v95 offset:64064
	ds_write_b16 v204, v99 offset:32832
	s_waitcnt vmcnt(4)
	v_mfma_f32_16x16x32_f16 v[52:55], v[40:43], v[76:79], 0
	v_mfma_f32_16x16x32_f16 v[48:51], v[44:47], v[76:79], 0
	v_mfma_f32_16x16x32_f16 v[52:55], v[32:35], v[80:83], v[52:55]
	v_mfma_f32_16x16x32_f16 v[48:51], v[36:39], v[80:83], v[48:51]
	v_mfma_f32_16x16x32_f16 v[52:55], v[24:27], v[84:87], v[52:55]
	v_mfma_f32_16x16x32_f16 v[48:51], v[28:31], v[84:87], v[48:51]
	v_mfma_f32_16x16x32_f16 v[52:55], v[20:23], v[88:91], v[52:55]
	v_mfma_f32_16x16x32_f16 v[48:51], v[16:19], v[88:91], v[48:51]
	global_load_dwordx4 v[76:79], v[170:171], off
	global_load_dwordx4 v[80:83], v[170:171], off offset:64
	global_load_dwordx4 v[84:87], v[170:171], off offset:128
	global_load_dwordx4 v[88:91], v[170:171], off offset:192
	s_nop 7
	s_nop 1
	v_cvt_f16_f32_e32 v92, v52
	v_cvt_f16_f32_e32 v96, v48
	v_cvt_f16_f32_e32 v93, v53
	v_cvt_f16_f32_e32 v97, v49
	v_cvt_f16_f32_e32 v94, v54
	v_cvt_f16_f32_e32 v98, v50
	v_cvt_f16_f32_e32 v95, v55
	v_cvt_f16_f32_e32 v99, v51
	ds_write_b16 v200, v92 offset:57952
	ds_write_b16 v201, v96 offset:32864
	ds_write_b16 v200, v93 offset:60000
	ds_write_b16 v202, v97 offset:32864
	ds_write_b16 v200, v94 offset:62048
	ds_write_b16 v203, v98 offset:32864
	ds_write_b16 v200, v95 offset:64096
	ds_write_b16 v204, v99 offset:32864
	s_waitcnt vmcnt(4)
	v_mfma_f32_16x16x32_f16 v[52:55], v[40:43], v[60:63], 0
	v_mfma_f32_16x16x32_f16 v[48:51], v[44:47], v[60:63], 0
	v_mfma_f32_16x16x32_f16 v[52:55], v[32:35], v[64:67], v[52:55]
	v_mfma_f32_16x16x32_f16 v[48:51], v[36:39], v[64:67], v[48:51]
	v_mfma_f32_16x16x32_f16 v[52:55], v[24:27], v[68:71], v[52:55]
	v_mfma_f32_16x16x32_f16 v[48:51], v[28:31], v[68:71], v[48:51]
	v_mfma_f32_16x16x32_f16 v[52:55], v[20:23], v[72:75], v[52:55]
	v_mfma_f32_16x16x32_f16 v[48:51], v[16:19], v[72:75], v[48:51]
	global_load_dwordx4 v[60:63], v[172:173], off
	global_load_dwordx4 v[64:67], v[172:173], off offset:64
	global_load_dwordx4 v[68:71], v[172:173], off offset:128
	global_load_dwordx4 v[72:75], v[172:173], off offset:192
	s_nop 7
	s_nop 1
	v_cvt_f16_f32_e32 v92, v52
	v_cvt_f16_f32_e32 v96, v48
	v_cvt_f16_f32_e32 v93, v53
	v_cvt_f16_f32_e32 v97, v49
	v_cvt_f16_f32_e32 v94, v54
	v_cvt_f16_f32_e32 v98, v50
	v_cvt_f16_f32_e32 v95, v55
	v_cvt_f16_f32_e32 v99, v51
	ds_write_b16 v200, v92 offset:57984
	ds_write_b16 v201, v96 offset:32896
	ds_write_b16 v200, v93 offset:60032
	ds_write_b16 v202, v97 offset:32896
	ds_write_b16 v200, v94 offset:62080
	ds_write_b16 v203, v98 offset:32896
	ds_write_b16 v200, v95 offset:64128
	ds_write_b16 v204, v99 offset:32896
	s_waitcnt vmcnt(4)
	v_mfma_f32_16x16x32_f16 v[52:55], v[40:43], v[76:79], 0
	v_mfma_f32_16x16x32_f16 v[48:51], v[44:47], v[76:79], 0
	v_mfma_f32_16x16x32_f16 v[52:55], v[32:35], v[80:83], v[52:55]
	v_mfma_f32_16x16x32_f16 v[48:51], v[36:39], v[80:83], v[48:51]
	v_mfma_f32_16x16x32_f16 v[52:55], v[24:27], v[84:87], v[52:55]
	v_mfma_f32_16x16x32_f16 v[48:51], v[28:31], v[84:87], v[48:51]
	v_mfma_f32_16x16x32_f16 v[52:55], v[20:23], v[88:91], v[52:55]
	v_mfma_f32_16x16x32_f16 v[48:51], v[16:19], v[88:91], v[48:51]
	global_load_dwordx4 v[76:79], v[174:175], off
	global_load_dwordx4 v[80:83], v[174:175], off offset:64
	global_load_dwordx4 v[84:87], v[174:175], off offset:128
	global_load_dwordx4 v[88:91], v[174:175], off offset:192
	s_nop 7
	s_nop 1
	v_cvt_f16_f32_e32 v92, v52
	v_cvt_f16_f32_e32 v96, v48
	v_cvt_f16_f32_e32 v93, v53
	v_cvt_f16_f32_e32 v97, v49
	v_cvt_f16_f32_e32 v94, v54
	v_cvt_f16_f32_e32 v98, v50
	v_cvt_f16_f32_e32 v95, v55
	v_cvt_f16_f32_e32 v99, v51
	ds_write_b16 v200, v92 offset:58016
	ds_write_b16 v201, v96 offset:32928
	ds_write_b16 v200, v93 offset:60064
	ds_write_b16 v202, v97 offset:32928
	ds_write_b16 v200, v94 offset:62112
	ds_write_b16 v203, v98 offset:32928
	ds_write_b16 v200, v95 offset:64160
	ds_write_b16 v204, v99 offset:32928
	s_waitcnt vmcnt(4)
	v_mfma_f32_16x16x32_f16 v[52:55], v[40:43], v[60:63], 0
	v_mfma_f32_16x16x32_f16 v[48:51], v[44:47], v[60:63], 0
	v_mfma_f32_16x16x32_f16 v[52:55], v[32:35], v[64:67], v[52:55]
	v_mfma_f32_16x16x32_f16 v[48:51], v[36:39], v[64:67], v[48:51]
	v_mfma_f32_16x16x32_f16 v[52:55], v[24:27], v[68:71], v[52:55]
	v_mfma_f32_16x16x32_f16 v[48:51], v[28:31], v[68:71], v[48:51]
	v_mfma_f32_16x16x32_f16 v[52:55], v[20:23], v[72:75], v[52:55]
	v_mfma_f32_16x16x32_f16 v[48:51], v[16:19], v[72:75], v[48:51]
	s_nop 7
	s_nop 1
	v_cvt_f16_f32_e32 v92, v52
	v_cvt_f16_f32_e32 v96, v48
	v_cvt_f16_f32_e32 v93, v53
	v_cvt_f16_f32_e32 v97, v49
	v_cvt_f16_f32_e32 v94, v54
	v_cvt_f16_f32_e32 v98, v50
	v_cvt_f16_f32_e32 v95, v55
	v_cvt_f16_f32_e32 v99, v51
	ds_write_b16 v200, v92 offset:58048
	ds_write_b16 v201, v96 offset:32960
	ds_write_b16 v200, v93 offset:60096
	ds_write_b16 v202, v97 offset:32960
	ds_write_b16 v200, v94 offset:62144
	ds_write_b16 v203, v98 offset:32960
	ds_write_b16 v200, v95 offset:64192
	ds_write_b16 v204, v99 offset:32960
	s_waitcnt vmcnt(0)
	v_mfma_f32_16x16x32_f16 v[52:55], v[40:43], v[76:79], 0
	v_mfma_f32_16x16x32_f16 v[48:51], v[44:47], v[76:79], 0
	v_mfma_f32_16x16x32_f16 v[52:55], v[32:35], v[80:83], v[52:55]
	v_mfma_f32_16x16x32_f16 v[48:51], v[36:39], v[80:83], v[48:51]
	v_mfma_f32_16x16x32_f16 v[52:55], v[24:27], v[84:87], v[52:55]
	v_mfma_f32_16x16x32_f16 v[48:51], v[28:31], v[84:87], v[48:51]
	v_mfma_f32_16x16x32_f16 v[52:55], v[20:23], v[88:91], v[52:55]
	v_mfma_f32_16x16x32_f16 v[48:51], v[16:19], v[88:91], v[48:51]
	s_nop 7
	s_nop 1
	v_cvt_f16_f32_e32 v92, v52
	v_cvt_f16_f32_e32 v96, v48
	v_cvt_f16_f32_e32 v93, v53
	v_cvt_f16_f32_e32 v97, v49
	v_cvt_f16_f32_e32 v94, v54
	v_cvt_f16_f32_e32 v98, v50
	v_cvt_f16_f32_e32 v95, v55
	v_cvt_f16_f32_e32 v99, v51
	ds_write_b16 v200, v92 offset:58080
	ds_write_b16 v201, v96 offset:32992
	ds_write_b16 v200, v93 offset:60128
	ds_write_b16 v202, v97 offset:32992
	ds_write_b16 v200, v94 offset:62176
	ds_write_b16 v203, v98 offset:32992
	ds_write_b16 v200, v95 offset:64224
	ds_write_b16 v204, v99 offset:32992
	v_and_b32_e32 v17, 64, v235
	v_add_u32_e32 v17, 64, v17
	v_xor_b32_e32 v16, 1, v235
	v_cmp_lt_i32_e32 vcc, v16, v17
	s_waitcnt lgkmcnt(0)
	s_barrier
	v_cndmask_b32_e32 v16, v235, v16, vcc
	v_lshlrev_b32_e32 v185, 2, v16
	v_xor_b32_e32 v16, 2, v235
	v_cmp_lt_i32_e32 vcc, v16, v17
	s_nop 1
	v_cndmask_b32_e32 v16, v235, v16, vcc
	v_lshlrev_b32_e32 v187, 2, v16
	v_xor_b32_e32 v16, 4, v235
	v_cmp_lt_i32_e32 vcc, v16, v17
	s_nop 1
	v_cndmask_b32_e32 v16, v235, v16, vcc
	v_lshlrev_b32_e32 v210, 2, v16
	ds_read_b128 v[16:19], v205
	ds_read_b128 v[20:23], v205 offset:16
	ds_read_b128 v[24:27], v205 offset:4096
	ds_read_b128 v[28:31], v205 offset:8192
	ds_read_b128 v[32:35], v205 offset:12288
	ds_read_b128 v[36:39], v205 offset:16384
	ds_read_b128 v[40:43], v205 offset:20480
	ds_read_b128 v[44:47], v205 offset:45056
	ds_read_b128 v[48:51], v205 offset:4112
	ds_read_b128 v[52:55], v205 offset:8208
	ds_read_b128 v[56:59], v205 offset:12304
	ds_read_b128 v[60:63], v205 offset:16400
	ds_read_b128 v[64:67], v205 offset:20496
	ds_read_b128 v[68:71], v205 offset:45072
	ds_read_b128 v[72:75], v205 offset:24576
	ds_read_b128 v[76:79], v205 offset:28672
	ds_read_b128 v[80:83], v205 offset:32768
	ds_read_b128 v[84:87], v209 offset:36864
	ds_read_b128 v[88:91], v209 offset:36880
	ds_read_b128 v[92:95], v209 offset:40960
	ds_read_b128 v[96:99], v205 offset:24592
	ds_read_b128 v[100:103], v205 offset:28688
	ds_read_b128 v[104:107], v205 offset:32784
	ds_read_b128 v[108:111], v209 offset:40976
	s_branch .LBB0_135
